# P2 RoPE epilogue: cos/sin loads of the eight row groups requested ahead (groups 1-3 with group 0, groups 4-6 during group 3) into dead K-loop fragment registers instead of seven serial round trips; on
# baseline (speedup 1.0000x reference)
.LBB0_305:
	s_lshl_b32 s11, s74, 8
	v_cndmask_b32_e64 v2, 0, 1, s[90:91]
	v_cmp_ne_u32_e64 s[6:7], 1, v2
	s_andn2_b64 vcc, exec, s[90:91]
	s_add_i32 s11, s11, s93
	s_cbranch_vccnz .LBB0_308
	s_bfe_u32 s18, s11, 0x50006
	v_mov_b32_e32 v2, s18
	v_cndmask_b32_e64 v2, v1, v2, s[2:3]
	v_lshlrev_b32_e32 v188, 7, v2
	v_lshl_add_u64 v[2:3], v[190:191], 0, v[188:189]
	v_lshl_add_u64 v[4:5], v[192:193], 0, v[188:189]
	global_load_dwordx4 v[18:21], v[2:3], off
	global_load_dwordx4 v[26:29], v[4:5], off
	v_mov_b32_e32 v247, 0
	v_mov_b32_e32 v246, s18
	v_cndmask_b32_e64 v246, v209, v246, s[2:3]
	v_lshlrev_b32_e32 v246, 7, v246
	v_lshl_add_u64 v[222:223], v[192:193], 0, v[246:247]
	v_lshl_add_u64 v[226:227], v[190:191], 0, v[246:247]
	global_load_dwordx4 v[222:225], v[222:223], off
	global_load_dwordx4 v[226:229], v[226:227], off
	v_mov_b32_e32 v246, s18
	v_cndmask_b32_e64 v246, v210, v246, s[2:3]
	v_lshlrev_b32_e32 v246, 7, v246
	v_lshl_add_u64 v[230:231], v[192:193], 0, v[246:247]
	v_lshl_add_u64 v[234:235], v[190:191], 0, v[246:247]
	global_load_dwordx4 v[230:233], v[230:231], off
	global_load_dwordx4 v[234:237], v[234:235], off
	v_mov_b32_e32 v246, s18
	v_cndmask_b32_e64 v246, v211, v246, s[2:3]
	v_lshlrev_b32_e32 v246, 7, v246
	v_lshl_add_u64 v[238:239], v[192:193], 0, v[246:247]
	v_lshl_add_u64 v[242:243], v[190:191], 0, v[246:247]
	global_load_dwordx4 v[238:241], v[238:239], off
	global_load_dwordx4 v[242:245], v[242:243], off
	s_and_b64 vcc, exec, s[6:7]
	s_cbranch_vccz .LBB0_309

.LBB0_309:
	s_bfe_u32 s18, s11, 0x50006
	s_waitcnt vmcnt(0)
	v_mov_b64_e32 v[30:31], v[222:223]
	v_mov_b64_e32 v[32:33], v[224:225]
	v_mov_b64_e32 v[22:23], v[226:227]
	v_mov_b64_e32 v[24:25], v[228:229]
	v_mov_b32_e32 v14, v30
	v_mov_b32_e32 v15, v31
	v_mov_b32_e32 v16, v32
	v_mov_b32_e32 v17, v33
	v_mov_b32_e32 v6, v22
	v_mov_b32_e32 v7, v23
	v_mov_b32_e32 v8, v24
	v_mov_b32_e32 v9, v25
.LBB0_310:
	v_add_u32_e32 v2, s79, v207
	v_or_b32_e32 v217, s11, v1
	v_ashrrev_i32_e32 v3, 31, v2
	v_lshl_add_u64 v[204:205], v[2:3], 1, s[88:89]
	v_mad_i64_i32 v[2:3], s[18:19], s86, v217, 0
	v_lshl_add_u64 v[10:11], v[2:3], 1, v[204:205]
	s_waitcnt vmcnt(0)
	v_pk_mul_f32 v[2:3], v[172:173], v[28:29]
	v_pk_mul_f32 v[4:5], v[170:171], v[26:27]
	v_pk_fma_f32 v[2:3], v[176:177], v[20:21], v[2:3] neg_lo:[0,0,1] neg_hi:[0,0,1]
	v_pk_fma_f32 v[4:5], v[174:175], v[18:19], v[4:5] neg_lo:[0,0,1] neg_hi:[0,0,1]
	v_pk_mul_f32 v[12:13], s[84:85], v[2:3] op_sel_hi:[0,1]
	v_pk_mul_f32 v[2:3], s[84:85], v[4:5] op_sel_hi:[0,1]
	v_pk_mul_f32 v[4:5], v[172:173], v[20:21]
	v_pk_mul_f32 v[34:35], v[170:171], v[18:19]
	v_pk_fma_f32 v[4:5], v[176:177], v[28:29], v[4:5]
	v_pk_fma_f32 v[34:35], v[174:175], v[26:27], v[34:35]
	v_pk_mul_f32 v[36:37], s[84:85], v[4:5] op_sel_hi:[0,1]
	v_pk_mul_f32 v[4:5], s[84:85], v[34:35] op_sel_hi:[0,1]
	v_cvt_pk_bf16_f32 v2, v2, v3
	v_cvt_pk_bf16_f32 v3, v12, v13
	v_cvt_pk_bf16_f32 v4, v4, v5
	v_cvt_pk_bf16_f32 v5, v36, v37
	global_store_dwordx4 v[10:11], v[2:5], off
	v_pk_mul_f32 v[34:35], v[158:159], v[18:19]
	s_and_b64 vcc, exec, s[6:7]
	v_pk_mul_f32 v[2:3], v[160:161], v[28:29]
	v_pk_mul_f32 v[4:5], v[158:159], v[26:27]
	v_pk_fma_f32 v[2:3], v[168:169], v[20:21], v[2:3] neg_lo:[0,0,1] neg_hi:[0,0,1]
	v_pk_fma_f32 v[4:5], v[166:167], v[18:19], v[4:5] neg_lo:[0,0,1] neg_hi:[0,0,1]
	v_pk_mul_f32 v[12:13], s[84:85], v[2:3] op_sel_hi:[0,1]
	v_pk_mul_f32 v[2:3], s[84:85], v[4:5] op_sel_hi:[0,1]
	v_pk_mul_f32 v[4:5], v[160:161], v[20:21]
	v_pk_fma_f32 v[34:35], v[166:167], v[26:27], v[34:35]
	v_pk_fma_f32 v[4:5], v[168:169], v[28:29], v[4:5]
	v_cvt_pk_bf16_f32 v2, v2, v3
	v_pk_mul_f32 v[36:37], s[84:85], v[4:5] op_sel_hi:[0,1]
	v_pk_mul_f32 v[4:5], s[84:85], v[34:35] op_sel_hi:[0,1]
	v_cvt_pk_bf16_f32 v3, v12, v13
	v_cvt_pk_bf16_f32 v4, v4, v5
	v_cvt_pk_bf16_f32 v5, v36, v37
	global_store_dwordx4 v[10:11], v[2:5], off offset:256
	s_cbranch_vccnz .LBB0_312
	s_bfe_u32 s18, s11, 0x50006
	v_mov_b64_e32 v[10:11], v[230:231]
	v_mov_b64_e32 v[12:13], v[232:233]
	v_mov_b64_e32 v[2:3], v[234:235]
	v_mov_b64_e32 v[4:5], v[236:237]
	v_mov_b64_e32 v[32:33], v[16:17]
	v_mov_b64_e32 v[40:41], v[16:17]
	v_mov_b64_e32 v[24:25], v[8:9]
	v_mov_b64_e32 v[48:49], v[8:9]
	v_mov_b64_e32 v[30:31], v[14:15]
	v_mov_b64_e32 v[38:39], v[14:15]
	v_mov_b64_e32 v[22:23], v[6:7]
	v_mov_b64_e32 v[46:47], v[6:7]
	v_mov_b64_e32 v[28:29], v[12:13]
	v_mov_b64_e32 v[26:27], v[10:11]
	v_mov_b64_e32 v[36:37], v[12:13]
	v_mov_b64_e32 v[34:35], v[10:11]
	v_mov_b64_e32 v[20:21], v[4:5]
	v_mov_b64_e32 v[18:19], v[2:3]
	v_mov_b64_e32 v[44:45], v[4:5]
	v_mov_b64_e32 v[42:43], v[2:3]
	s_branch .LBB0_313

.LBB0_313:
	v_or_b32_e32 v2, 16, v217
	v_mad_i64_i32 v[2:3], s[18:19], s86, v2, 0
	v_lshl_add_u64 v[10:11], v[2:3], 1, v[204:205]
	v_pk_mul_f32 v[2:3], v[156:157], v[32:33]
	v_pk_mul_f32 v[4:5], v[154:155], v[30:31]
	s_mov_b32 s85, s84
	v_pk_fma_f32 v[4:5], v[162:163], v[22:23], v[4:5] neg_lo:[0,0,1] neg_hi:[0,0,1]
	v_pk_fma_f32 v[2:3], v[164:165], v[24:25], v[2:3] neg_lo:[0,0,1] neg_hi:[0,0,1]
	s_mov_b32 s88, s84
	s_mov_b32 s89, s84
	v_pk_mul_f32 v[12:13], s[88:89], v[2:3]
	v_pk_mul_f32 v[2:3], s[84:85], v[4:5]
	v_pk_mul_f32 v[4:5], v[156:157], v[24:25]
	v_pk_mul_f32 v[218:219], v[154:155], v[22:23]
	v_pk_fma_f32 v[4:5], v[164:165], v[32:33], v[4:5]
	v_pk_fma_f32 v[218:219], v[162:163], v[30:31], v[218:219]
	v_pk_mul_f32 v[220:221], s[88:89], v[4:5]
	v_pk_mul_f32 v[4:5], s[84:85], v[218:219]
	v_cvt_pk_bf16_f32 v2, v2, v3
	v_cvt_pk_bf16_f32 v3, v12, v13
	v_cvt_pk_bf16_f32 v4, v4, v5
	v_cvt_pk_bf16_f32 v5, v220, v221
	global_store_dwordx4 v[10:11], v[2:5], off
	v_pk_mul_f32 v[218:219], v[142:143], v[22:23]
	s_and_b64 vcc, exec, s[6:7]
	v_pk_mul_f32 v[2:3], v[144:145], v[32:33]
	v_pk_mul_f32 v[4:5], v[142:143], v[30:31]
	v_pk_fma_f32 v[2:3], v[152:153], v[24:25], v[2:3] neg_lo:[0,0,1] neg_hi:[0,0,1]
	v_pk_fma_f32 v[4:5], v[150:151], v[22:23], v[4:5] neg_lo:[0,0,1] neg_hi:[0,0,1]
	v_pk_mul_f32 v[12:13], s[88:89], v[2:3]
	v_pk_mul_f32 v[2:3], s[84:85], v[4:5]
	v_pk_mul_f32 v[4:5], v[144:145], v[24:25]
	v_pk_fma_f32 v[218:219], v[150:151], v[30:31], v[218:219]
	v_pk_fma_f32 v[4:5], v[152:153], v[32:33], v[4:5]
	v_cvt_pk_bf16_f32 v2, v2, v3
	v_pk_mul_f32 v[220:221], s[88:89], v[4:5]
	v_pk_mul_f32 v[4:5], s[84:85], v[218:219]
	v_cvt_pk_bf16_f32 v3, v12, v13
	v_cvt_pk_bf16_f32 v4, v4, v5
	v_cvt_pk_bf16_f32 v5, v220, v221
	global_store_dwordx4 v[10:11], v[2:5], off offset:256
	s_cbranch_vccnz .LBB0_315
	s_bfe_u32 s11, s11, 0x50006
	v_mov_b64_e32 v[6:7], v[242:243]
	v_mov_b64_e32 v[8:9], v[244:245]
	v_mov_b64_e32 v[14:15], v[238:239]
	v_mov_b64_e32 v[16:17], v[240:241]
	v_mov_b64_e32 v[18:19], v[42:43]
	v_mov_b64_e32 v[26:27], v[34:35]
	v_mov_b64_e32 v[22:23], v[46:47]
	v_mov_b64_e32 v[24:25], v[48:49]
	v_mov_b64_e32 v[30:31], v[38:39]
	v_mov_b64_e32 v[32:33], v[40:41]
	v_mov_b64_e32 v[20:21], v[44:45]
	v_mov_b64_e32 v[28:29], v[36:37]
	v_mov_b32_e32 v22, v6
	v_mov_b32_e32 v23, v7
	v_mov_b32_e32 v24, v8
	v_mov_b32_e32 v25, v9
	v_mov_b32_e32 v247, 0
	v_add_u32_e32 v246, 0x80, v217
	v_bfe_u32 v246, v246, 6, 5
	v_cndmask_b32_e64 v222, v1, v246, s[2:3]
	v_lshlrev_b32_e32 v222, 7, v222
	v_mov_b32_e32 v223, v247
	v_lshl_add_u64 v[226:227], v[190:191], 0, v[222:223]
	v_lshl_add_u64 v[222:223], v[192:193], 0, v[222:223]
	global_load_dwordx4 v[222:225], v[222:223], off
	global_load_dwordx4 v[226:229], v[226:227], off
	v_cndmask_b32_e64 v230, v209, v246, s[2:3]
	v_lshlrev_b32_e32 v230, 7, v230
	v_mov_b32_e32 v231, v247
	v_lshl_add_u64 v[234:235], v[190:191], 0, v[230:231]
	v_lshl_add_u64 v[230:231], v[192:193], 0, v[230:231]
	global_load_dwordx4 v[230:233], v[230:231], off
	global_load_dwordx4 v[234:237], v[234:235], off
	v_cndmask_b32_e64 v238, v210, v246, s[2:3]
	v_lshlrev_b32_e32 v238, 7, v238
	v_mov_b32_e32 v239, v247
	v_lshl_add_u64 v[242:243], v[190:191], 0, v[238:239]
	v_lshl_add_u64 v[238:239], v[192:193], 0, v[238:239]
	global_load_dwordx4 v[238:241], v[238:239], off
	global_load_dwordx4 v[242:245], v[242:243], off
	v_mov_b32_e32 v30, v14
	v_mov_b32_e32 v31, v15
	v_mov_b32_e32 v32, v16
	v_mov_b32_e32 v33, v17
.LBB0_315:
	s_nop 0
	v_or_b32_e32 v2, 32, v217
	v_mad_i64_i32 v[2:3], s[18:19], s86, v2, 0
	v_lshl_add_u64 v[10:11], v[2:3], 1, v[204:205]
	v_pk_mul_f32 v[2:3], v[140:141], v[28:29]
	v_pk_mul_f32 v[4:5], v[138:139], v[26:27]
	v_pk_fma_f32 v[2:3], v[148:149], v[20:21], v[2:3] neg_lo:[0,0,1] neg_hi:[0,0,1]
	v_pk_fma_f32 v[4:5], v[146:147], v[18:19], v[4:5] neg_lo:[0,0,1] neg_hi:[0,0,1]
	v_pk_mul_f32 v[12:13], s[88:89], v[2:3]
	v_pk_mul_f32 v[2:3], s[84:85], v[4:5]
	v_pk_mul_f32 v[4:5], v[140:141], v[20:21]
	v_pk_mul_f32 v[218:219], v[138:139], v[18:19]
	v_pk_fma_f32 v[4:5], v[148:149], v[28:29], v[4:5]
	v_pk_fma_f32 v[218:219], v[146:147], v[26:27], v[218:219]
	v_pk_mul_f32 v[220:221], s[88:89], v[4:5]
	v_pk_mul_f32 v[4:5], s[84:85], v[218:219]
	v_cvt_pk_bf16_f32 v2, v2, v3
	v_cvt_pk_bf16_f32 v3, v12, v13
	v_cvt_pk_bf16_f32 v4, v4, v5
	v_cvt_pk_bf16_f32 v5, v220, v221
	global_store_dwordx4 v[10:11], v[2:5], off
	v_pk_mul_f32 v[218:219], v[126:127], v[18:19]
	v_add_u32_e32 v215, 0x80, v217
	v_pk_mul_f32 v[2:3], v[128:129], v[28:29]
	v_pk_mul_f32 v[4:5], v[126:127], v[26:27]
	v_pk_fma_f32 v[2:3], v[136:137], v[20:21], v[2:3] neg_lo:[0,0,1] neg_hi:[0,0,1]
	v_pk_fma_f32 v[4:5], v[134:135], v[18:19], v[4:5] neg_lo:[0,0,1] neg_hi:[0,0,1]
	v_pk_mul_f32 v[12:13], s[88:89], v[2:3]
	v_pk_mul_f32 v[2:3], s[84:85], v[4:5]
	v_pk_mul_f32 v[4:5], v[128:129], v[20:21]
	v_pk_fma_f32 v[218:219], v[134:135], v[26:27], v[218:219]
	v_pk_fma_f32 v[4:5], v[136:137], v[28:29], v[4:5]
	v_cvt_pk_bf16_f32 v2, v2, v3
	v_pk_mul_f32 v[220:221], s[88:89], v[4:5]
	v_pk_mul_f32 v[4:5], s[84:85], v[218:219]
	v_cvt_pk_bf16_f32 v3, v12, v13
	v_cvt_pk_bf16_f32 v4, v4, v5
	v_cvt_pk_bf16_f32 v5, v220, v221
	global_store_dwordx4 v[10:11], v[2:5], off offset:256
	s_and_b64 vcc, exec, s[6:7]
	v_bfe_u32 v216, v215, 6, 5
	s_cbranch_vccnz .LBB0_317
	s_waitcnt vmcnt(4)
	v_mov_b64_e32 v[10:11], v[222:223]
	v_mov_b64_e32 v[12:13], v[224:225]
	v_mov_b64_e32 v[2:3], v[226:227]
	v_mov_b64_e32 v[4:5], v[228:229]
	v_mov_b64_e32 v[32:33], v[16:17]
	v_mov_b64_e32 v[40:41], v[16:17]
	v_mov_b64_e32 v[24:25], v[8:9]
	v_mov_b64_e32 v[48:49], v[8:9]
	v_mov_b64_e32 v[30:31], v[14:15]
	v_mov_b64_e32 v[38:39], v[14:15]
	v_mov_b64_e32 v[22:23], v[6:7]
	v_mov_b64_e32 v[46:47], v[6:7]
	v_mov_b64_e32 v[28:29], v[12:13]
	v_mov_b64_e32 v[26:27], v[10:11]
	v_mov_b64_e32 v[36:37], v[12:13]
	v_mov_b64_e32 v[34:35], v[10:11]
	v_mov_b64_e32 v[20:21], v[4:5]
	v_mov_b64_e32 v[18:19], v[2:3]
	v_mov_b64_e32 v[44:45], v[4:5]
	v_mov_b64_e32 v[42:43], v[2:3]
.LBB0_317:
	v_or_b32_e32 v2, 48, v217
	v_mad_i64_i32 v[2:3], s[18:19], s86, v2, 0
	v_lshl_add_u64 v[10:11], v[2:3], 1, v[204:205]
	v_pk_mul_f32 v[2:3], v[124:125], v[32:33]
	v_pk_mul_f32 v[4:5], v[122:123], v[30:31]
	v_pk_fma_f32 v[2:3], v[132:133], v[24:25], v[2:3] neg_lo:[0,0,1] neg_hi:[0,0,1]
	v_pk_fma_f32 v[4:5], v[130:131], v[22:23], v[4:5] neg_lo:[0,0,1] neg_hi:[0,0,1]
	s_mov_b32 s88, s84
	s_mov_b32 s89, s84
	v_pk_mul_f32 v[12:13], s[88:89], v[2:3]
	v_pk_mul_f32 v[2:3], s[84:85], v[4:5]
	v_pk_mul_f32 v[4:5], v[124:125], v[24:25]
	v_pk_mul_f32 v[218:219], v[122:123], v[22:23]
	v_pk_fma_f32 v[4:5], v[132:133], v[32:33], v[4:5]
	v_pk_fma_f32 v[218:219], v[130:131], v[30:31], v[218:219]
	v_pk_mul_f32 v[220:221], s[88:89], v[4:5]
	v_pk_mul_f32 v[4:5], s[84:85], v[218:219]
	v_cvt_pk_bf16_f32 v2, v2, v3
	v_cvt_pk_bf16_f32 v3, v12, v13
	v_cvt_pk_bf16_f32 v4, v4, v5
	v_cvt_pk_bf16_f32 v5, v220, v221
	global_store_dwordx4 v[10:11], v[2:5], off
	v_pk_mul_f32 v[218:219], v[114:115], v[22:23]
	s_and_b64 vcc, exec, s[6:7]
	v_pk_mul_f32 v[2:3], v[116:117], v[32:33]
	v_pk_mul_f32 v[4:5], v[114:115], v[30:31]
	v_pk_fma_f32 v[2:3], v[120:121], v[24:25], v[2:3] neg_lo:[0,0,1] neg_hi:[0,0,1]
	v_pk_fma_f32 v[4:5], v[118:119], v[22:23], v[4:5] neg_lo:[0,0,1] neg_hi:[0,0,1]
	v_pk_mul_f32 v[12:13], s[88:89], v[2:3]
	v_pk_mul_f32 v[2:3], s[84:85], v[4:5]
	v_pk_mul_f32 v[4:5], v[116:117], v[24:25]
	v_pk_fma_f32 v[218:219], v[118:119], v[30:31], v[218:219]
	v_pk_fma_f32 v[4:5], v[120:121], v[32:33], v[4:5]
	v_cvt_pk_bf16_f32 v2, v2, v3
	v_pk_mul_f32 v[220:221], s[88:89], v[4:5]
	v_pk_mul_f32 v[4:5], s[84:85], v[218:219]
	v_cvt_pk_bf16_f32 v3, v12, v13
	v_cvt_pk_bf16_f32 v4, v4, v5
	v_cvt_pk_bf16_f32 v5, v220, v221
	global_store_dwordx4 v[10:11], v[2:5], off offset:256
	s_cbranch_vccnz .LBB0_319
	s_nop 0
	s_waitcnt vmcnt(4)
	v_mov_b64_e32 v[6:7], v[234:235]
	v_mov_b64_e32 v[8:9], v[236:237]
	v_mov_b64_e32 v[14:15], v[230:231]
	v_mov_b64_e32 v[16:17], v[232:233]
	v_mov_b64_e32 v[18:19], v[42:43]
	v_mov_b64_e32 v[26:27], v[34:35]
	v_mov_b64_e32 v[22:23], v[46:47]
	v_mov_b64_e32 v[24:25], v[48:49]
	v_mov_b64_e32 v[30:31], v[38:39]
	v_mov_b64_e32 v[32:33], v[40:41]
	v_mov_b64_e32 v[20:21], v[44:45]
	v_mov_b64_e32 v[28:29], v[36:37]
	v_mov_b32_e32 v22, v6
	v_mov_b32_e32 v23, v7
	v_mov_b32_e32 v24, v8
	v_mov_b32_e32 v25, v9
	v_mov_b32_e32 v30, v14
	v_mov_b32_e32 v31, v15
	v_mov_b32_e32 v32, v16
	v_mov_b32_e32 v33, v17
.LBB0_319:
	s_nop 0
	v_mad_i64_i32 v[2:3], s[18:19], s86, v215, 0
	v_lshl_add_u64 v[10:11], v[2:3], 1, v[204:205]
	v_pk_mul_f32 v[2:3], v[108:109], v[28:29]
	v_pk_mul_f32 v[4:5], v[106:107], v[26:27]
	v_pk_fma_f32 v[2:3], v[112:113], v[20:21], v[2:3] neg_lo:[0,0,1] neg_hi:[0,0,1]
	v_pk_fma_f32 v[4:5], v[110:111], v[18:19], v[4:5] neg_lo:[0,0,1] neg_hi:[0,0,1]
	v_pk_mul_f32 v[12:13], s[88:89], v[2:3]
	v_pk_mul_f32 v[2:3], s[84:85], v[4:5]
	v_pk_mul_f32 v[4:5], v[108:109], v[20:21]
	v_pk_mul_f32 v[38:39], v[106:107], v[18:19]
	v_pk_fma_f32 v[4:5], v[112:113], v[28:29], v[4:5]
	v_pk_fma_f32 v[38:39], v[110:111], v[26:27], v[38:39]
	v_pk_mul_f32 v[40:41], s[88:89], v[4:5]
	v_pk_mul_f32 v[4:5], s[84:85], v[38:39]
	v_cvt_pk_bf16_f32 v2, v2, v3
	v_cvt_pk_bf16_f32 v3, v12, v13
	v_cvt_pk_bf16_f32 v4, v4, v5
	v_cvt_pk_bf16_f32 v5, v40, v41
	global_store_dwordx4 v[10:11], v[2:5], off
	v_pk_mul_f32 v[38:39], v[94:95], v[18:19]
	s_and_b64 vcc, exec, s[6:7]
	v_pk_mul_f32 v[2:3], v[96:97], v[28:29]
	v_pk_mul_f32 v[4:5], v[94:95], v[26:27]
	v_pk_fma_f32 v[2:3], v[104:105], v[20:21], v[2:3] neg_lo:[0,0,1] neg_hi:[0,0,1]
	v_pk_fma_f32 v[4:5], v[102:103], v[18:19], v[4:5] neg_lo:[0,0,1] neg_hi:[0,0,1]
	v_pk_mul_f32 v[12:13], s[88:89], v[2:3]
	v_pk_mul_f32 v[2:3], s[84:85], v[4:5]
	v_pk_mul_f32 v[4:5], v[96:97], v[20:21]
	v_pk_fma_f32 v[38:39], v[102:103], v[26:27], v[38:39]
	v_pk_fma_f32 v[4:5], v[104:105], v[28:29], v[4:5]
	v_cvt_pk_bf16_f32 v2, v2, v3
	v_pk_mul_f32 v[40:41], s[88:89], v[4:5]
	v_pk_mul_f32 v[4:5], s[84:85], v[38:39]
	v_cvt_pk_bf16_f32 v3, v12, v13
	v_cvt_pk_bf16_f32 v4, v4, v5
	v_cvt_pk_bf16_f32 v5, v40, v41
	global_store_dwordx4 v[10:11], v[2:5], off offset:256
	s_cbranch_vccnz .LBB0_321
	s_nop 0
	s_waitcnt vmcnt(4)
	v_mov_b64_e32 v[10:11], v[238:239]
	v_mov_b64_e32 v[12:13], v[240:241]
	v_mov_b64_e32 v[2:3], v[242:243]
	v_mov_b64_e32 v[4:5], v[244:245]
	v_mov_b64_e32 v[32:33], v[16:17]
	v_mov_b64_e32 v[40:41], v[16:17]
	v_mov_b64_e32 v[24:25], v[8:9]
	v_mov_b64_e32 v[48:49], v[8:9]
	v_mov_b64_e32 v[30:31], v[14:15]
	v_mov_b64_e32 v[22:23], v[6:7]
	v_mov_b64_e32 v[38:39], v[14:15]
	v_mov_b64_e32 v[46:47], v[6:7]
	v_mov_b64_e32 v[28:29], v[12:13]
	v_mov_b64_e32 v[26:27], v[10:11]
	v_mov_b64_e32 v[36:37], v[12:13]
	v_mov_b64_e32 v[34:35], v[10:11]
	v_mov_b64_e32 v[20:21], v[4:5]
	v_mov_b64_e32 v[18:19], v[2:3]
	v_mov_b64_e32 v[44:45], v[4:5]
	v_mov_b64_e32 v[42:43], v[2:3]
